# HGRN2: waves 4-7 start step 2b 256 cycles late (stagger against their SIMD partners)
# speedup vs baseline: 1.0116x; 1.0034x over previous
.LBB0_1173:
	s_cmp_lt_u32 s20, 4
	s_cbranch_scc1 .Lhg_nostag
	s_sleep 4
